# f32 weight loads of the bf16 conversion loops marked nt (read once; keep L2/MALL for GEMM operands)
# speedup vs baseline: 1.0200x; 1.0042x over previous
.LBB0_21:
	s_mul_hi_i32 s28, s30, 0x2e8ba2e9
	s_lshr_b32 s29, s28, 31
	s_ashr_i32 s28, s28, 4
	s_add_i32 s29, s28, s29
	s_lshl_b32 s28, s29, 6
	s_mul_i32 s31, s29, 0xffffea00
	s_mulk_i32 s29, 0xf500
	s_bfe_i32 s34, s30, 0x10001
	s_add_i32 s29, s13, s29
	s_add_i32 s31, s3, s31
	s_and_b32 s34, s34, 0xb00
	s_and_b32 s29, s29, 0xffffff80
	s_add_i32 s34, s34, s29
	s_and_b32 s29, s31, 64
	s_or_b32 s29, s29, s34
	v_or_b32_e32 v0, s29, v71
	v_or_b32_e32 v68, s28, v70
	v_mad_i64_i32 v[2:3], s[34:35], v68, s15, v[66:67]
	v_ashrrev_i32_e32 v1, 31, v0
	v_lshl_add_u64 v[40:41], v[0:1], 2, v[2:3]
	v_add_co_u32_e32 v0, vcc, s16, v40
	s_nop 1
	v_addc_co_u32_e32 v1, vcc, 0, v41, vcc
	v_add_co_u32_e32 v8, vcc, s17, v40
	global_load_dwordx4 v[4:7], v[40:41], off nt
	s_nop 0
	global_load_dwordx4 v[0:3], v[0:1], off nt
	v_addc_co_u32_e32 v9, vcc, 0, v41, vcc
	v_add_co_u32_e32 v10, vcc, s18, v40
	s_nop 1
	v_addc_co_u32_e32 v11, vcc, 0, v41, vcc
	v_add_co_u32_e32 v16, vcc, s19, v40
	global_load_dwordx4 v[12:15], v[8:9], off nt
	s_nop 0
	global_load_dwordx4 v[8:11], v[10:11], off nt
	v_addc_co_u32_e32 v17, vcc, 0, v41, vcc
	v_add_co_u32_e32 v18, vcc, s20, v40
	s_nop 1
	v_addc_co_u32_e32 v19, vcc, 0, v41, vcc
	v_add_co_u32_e32 v24, vcc, s21, v40
	global_load_dwordx4 v[20:23], v[16:17], off nt
	s_nop 0
	global_load_dwordx4 v[16:19], v[18:19], off nt
	v_addc_co_u32_e32 v25, vcc, 0, v41, vcc
	v_add_co_u32_e32 v26, vcc, s22, v40
	s_nop 1
	v_addc_co_u32_e32 v27, vcc, 0, v41, vcc
	v_add_co_u32_e32 v32, vcc, s23, v40
	global_load_dwordx4 v[28:31], v[24:25], off nt
	s_nop 0
	global_load_dwordx4 v[24:27], v[26:27], off nt
	v_addc_co_u32_e32 v33, vcc, 0, v41, vcc
	v_add_co_u32_e32 v34, vcc, s24, v40
	s_nop 1
	v_addc_co_u32_e32 v35, vcc, 0, v41, vcc
	v_add_co_u32_e32 v42, vcc, s25, v40
	global_load_dwordx4 v[36:39], v[32:33], off nt
	s_nop 0
	global_load_dwordx4 v[32:35], v[34:35], off nt
	v_addc_co_u32_e32 v43, vcc, 0, v41, vcc
	v_add_co_u32_e32 v44, vcc, s26, v40
	s_nop 1
	v_addc_co_u32_e32 v45, vcc, 0, v41, vcc
	v_add_co_u32_e32 v46, vcc, s27, v40
	s_nop 1
	v_addc_co_u32_e32 v47, vcc, 0, v41, vcc
	v_add_co_u32_e32 v48, vcc, 0x11e000, v40
	s_nop 1
	v_addc_co_u32_e32 v49, vcc, 0, v41, vcc
	v_add_co_u32_e32 v76, vcc, 0x134000, v40
	s_nop 1
	v_addc_co_u32_e32 v77, vcc, 0, v41, vcc
	v_add_co_u32_e32 v40, vcc, 0x14a000, v40
	s_nop 1
	v_addc_co_u32_e32 v41, vcc, 0, v41, vcc
	global_load_dwordx4 v[60:63], v[42:43], off nt
	global_load_dwordx4 v[56:59], v[44:45], off nt
	global_load_dwordx4 v[52:55], v[46:47], off nt
	s_nop 0
	global_load_dwordx4 v[48:51], v[48:49], off nt
	s_nop 0
	global_load_dwordx4 v[44:47], v[76:77], off nt
	s_nop 0
	global_load_dwordx4 v[40:43], v[40:41], off nt
	s_and_b64 vcc, exec, s[4:5]
	s_cbranch_vccnz .LBB0_20
	s_load_dwordx16 s[44:59], s[0:1], 0x0
	v_ashrrev_i32_e32 v69, 31, v68
	s_waitcnt lgkmcnt(0)
	v_lshl_add_u64 v[68:69], v[68:69], 2, s[46:47]
	global_load_dword v76, v[68:69], off
	global_load_dword v78, v[68:69], off offset:16
	global_load_dword v80, v[68:69], off offset:32
	global_load_dword v82, v[68:69], off offset:48
	global_load_dword v84, v[68:69], off offset:64
	global_load_dword v86, v[68:69], off offset:80
	global_load_dword v88, v[68:69], off offset:96
	global_load_dword v90, v[68:69], off offset:112
	global_load_dword v92, v[68:69], off offset:128
	global_load_dword v94, v[68:69], off offset:144
	global_load_dword v96, v[68:69], off offset:160
	global_load_dword v98, v[68:69], off offset:176
	global_load_dword v100, v[68:69], off offset:192
	global_load_dword v102, v[68:69], off offset:208
	global_load_dword v104, v[68:69], off offset:224
	s_nop 0
	global_load_dword v68, v[68:69], off offset:240
	s_waitcnt vmcnt(15)
	v_pk_mul_f32 v[6:7], v[6:7], v[76:77] op_sel_hi:[1,0]
	v_pk_mul_f32 v[4:5], v[4:5], v[76:77] op_sel_hi:[1,0]
	s_waitcnt vmcnt(14)
	v_pk_mul_f32 v[2:3], v[2:3], v[78:79] op_sel_hi:[1,0]
	v_pk_mul_f32 v[0:1], v[0:1], v[78:79] op_sel_hi:[1,0]
	s_waitcnt vmcnt(13)
	v_pk_mul_f32 v[14:15], v[14:15], v[80:81] op_sel_hi:[1,0]
	v_pk_mul_f32 v[12:13], v[12:13], v[80:81] op_sel_hi:[1,0]
	s_waitcnt vmcnt(12)
	v_pk_mul_f32 v[10:11], v[10:11], v[82:83] op_sel_hi:[1,0]
	v_pk_mul_f32 v[8:9], v[8:9], v[82:83] op_sel_hi:[1,0]
	s_waitcnt vmcnt(11)
	v_pk_mul_f32 v[22:23], v[22:23], v[84:85] op_sel_hi:[1,0]
	v_pk_mul_f32 v[20:21], v[20:21], v[84:85] op_sel_hi:[1,0]
	s_waitcnt vmcnt(10)
	v_pk_mul_f32 v[18:19], v[18:19], v[86:87] op_sel_hi:[1,0]
	v_pk_mul_f32 v[16:17], v[16:17], v[86:87] op_sel_hi:[1,0]
	s_waitcnt vmcnt(9)
	v_pk_mul_f32 v[30:31], v[30:31], v[88:89] op_sel_hi:[1,0]
	v_pk_mul_f32 v[28:29], v[28:29], v[88:89] op_sel_hi:[1,0]
	s_waitcnt vmcnt(8)
	v_pk_mul_f32 v[26:27], v[26:27], v[90:91] op_sel_hi:[1,0]
	v_pk_mul_f32 v[24:25], v[24:25], v[90:91] op_sel_hi:[1,0]
	s_waitcnt vmcnt(7)
	v_pk_mul_f32 v[38:39], v[38:39], v[92:93] op_sel_hi:[1,0]
	v_pk_mul_f32 v[36:37], v[36:37], v[92:93] op_sel_hi:[1,0]
	s_waitcnt vmcnt(6)
	v_pk_mul_f32 v[34:35], v[34:35], v[94:95] op_sel_hi:[1,0]
	v_pk_mul_f32 v[32:33], v[32:33], v[94:95] op_sel_hi:[1,0]
	s_waitcnt vmcnt(5)
	v_pk_mul_f32 v[62:63], v[62:63], v[96:97] op_sel_hi:[1,0]
	v_pk_mul_f32 v[60:61], v[60:61], v[96:97] op_sel_hi:[1,0]
	s_waitcnt vmcnt(4)
	v_pk_mul_f32 v[58:59], v[58:59], v[98:99] op_sel_hi:[1,0]
	v_pk_mul_f32 v[56:57], v[56:57], v[98:99] op_sel_hi:[1,0]
	s_waitcnt vmcnt(3)
	v_pk_mul_f32 v[54:55], v[54:55], v[100:101] op_sel_hi:[1,0]
	v_pk_mul_f32 v[52:53], v[52:53], v[100:101] op_sel_hi:[1,0]
	s_waitcnt vmcnt(2)
	v_pk_mul_f32 v[50:51], v[50:51], v[102:103] op_sel_hi:[1,0]
	v_pk_mul_f32 v[48:49], v[48:49], v[102:103] op_sel_hi:[1,0]
	s_waitcnt vmcnt(1)
	v_pk_mul_f32 v[46:47], v[46:47], v[104:105] op_sel_hi:[1,0]
	v_pk_mul_f32 v[44:45], v[44:45], v[104:105] op_sel_hi:[1,0]
	s_waitcnt vmcnt(0)
	v_pk_mul_f32 v[42:43], v[42:43], v[68:69] op_sel_hi:[1,0]
	v_pk_mul_f32 v[40:41], v[40:41], v[68:69] op_sel_hi:[1,0]
	s_branch .LBB0_20

.LBB0_240:
	s_lshl_b32 s86, s17, 6
	v_or_b32_e32 v66, s86, v68
	v_ashrrev_i32_e32 v67, 31, v66
	v_mul_lo_u32 v1, s36, v67
	v_mul_lo_u32 v4, s37, v66
	v_mad_u64_u32 v[2:3], s[18:19], s36, v66, 0
	v_add3_u32 v3, v3, v1, v4
	v_lshl_add_u64 v[2:3], v[2:3], 2, s[90:91]
	v_ashrrev_i32_e32 v1, 31, v0
	v_lshl_add_u64 v[0:1], v[0:1], 2, v[2:3]
	s_lshl_b64 s[18:19], s[36:37], 4
	v_lshl_add_u64 v[2:3], v[0:1], 0, s[18:19]
	global_load_dwordx4 v[60:63], v[0:1], off nt
	global_load_dwordx4 v[56:59], v[2:3], off nt
	v_lshl_add_u64 v[0:1], v[2:3], 0, s[18:19]
	v_lshl_add_u64 v[2:3], v[0:1], 0, s[18:19]
	global_load_dwordx4 v[52:55], v[0:1], off nt
	global_load_dwordx4 v[48:51], v[2:3], off nt
	v_lshl_add_u64 v[0:1], v[2:3], 0, s[18:19]
	v_lshl_add_u64 v[2:3], v[0:1], 0, s[18:19]
	global_load_dwordx4 v[44:47], v[0:1], off nt
	global_load_dwordx4 v[40:43], v[2:3], off nt
	v_lshl_add_u64 v[0:1], v[2:3], 0, s[18:19]
	v_lshl_add_u64 v[2:3], v[0:1], 0, s[18:19]
	global_load_dwordx4 v[36:39], v[0:1], off nt
	global_load_dwordx4 v[32:35], v[2:3], off nt
	v_lshl_add_u64 v[0:1], v[2:3], 0, s[18:19]
	global_load_dwordx4 v[28:31], v[0:1], off nt
	v_lshl_add_u64 v[0:1], v[0:1], 0, s[18:19]
	global_load_dwordx4 v[24:27], v[0:1], off nt
	v_lshl_add_u64 v[0:1], v[0:1], 0, s[18:19]
	global_load_dwordx4 v[20:23], v[0:1], off nt
	v_lshl_add_u64 v[0:1], v[0:1], 0, s[18:19]
	global_load_dwordx4 v[16:19], v[0:1], off nt
	v_lshl_add_u64 v[0:1], v[0:1], 0, s[18:19]
	global_load_dwordx4 v[12:15], v[0:1], off nt
	v_lshl_add_u64 v[0:1], v[0:1], 0, s[18:19]
	global_load_dwordx4 v[8:11], v[0:1], off nt
	v_lshl_add_u64 v[0:1], v[0:1], 0, s[18:19]
	global_load_dwordx4 v[4:7], v[0:1], off nt
	v_lshl_add_u64 v[0:1], v[0:1], 0, s[18:19]
	global_load_dwordx4 v[0:3], v[0:1], off nt
	s_cmp_eq_u64 s[30:31], 0
	s_cbranch_scc1 .LBB0_121
	v_lshl_add_u64 v[66:67], v[66:67], 2, s[30:31]
	global_load_dword v82, v[66:67], off
	s_waitcnt vmcnt(0)
	v_pk_mul_f32 v[62:63], v[62:63], v[82:83] op_sel_hi:[1,0]
	v_pk_mul_f32 v[60:61], v[60:61], v[82:83] op_sel_hi:[1,0]
	global_load_dword v82, v[66:67], off offset:16
	s_waitcnt vmcnt(0)
	v_pk_mul_f32 v[58:59], v[58:59], v[82:83] op_sel_hi:[1,0]
	v_pk_mul_f32 v[56:57], v[56:57], v[82:83] op_sel_hi:[1,0]
	global_load_dword v82, v[66:67], off offset:32
	s_waitcnt vmcnt(0)
	v_pk_mul_f32 v[54:55], v[54:55], v[82:83] op_sel_hi:[1,0]
	v_pk_mul_f32 v[52:53], v[52:53], v[82:83] op_sel_hi:[1,0]
	global_load_dword v82, v[66:67], off offset:48
	s_waitcnt vmcnt(0)
	v_pk_mul_f32 v[50:51], v[50:51], v[82:83] op_sel_hi:[1,0]
	v_pk_mul_f32 v[48:49], v[48:49], v[82:83] op_sel_hi:[1,0]
	global_load_dword v82, v[66:67], off offset:64
	s_waitcnt vmcnt(0)
	v_pk_mul_f32 v[46:47], v[46:47], v[82:83] op_sel_hi:[1,0]
	v_pk_mul_f32 v[44:45], v[44:45], v[82:83] op_sel_hi:[1,0]
	global_load_dword v82, v[66:67], off offset:80
	s_waitcnt vmcnt(0)
	v_pk_mul_f32 v[42:43], v[42:43], v[82:83] op_sel_hi:[1,0]
	v_pk_mul_f32 v[40:41], v[40:41], v[82:83] op_sel_hi:[1,0]
	global_load_dword v82, v[66:67], off offset:96
	s_waitcnt vmcnt(0)
	v_pk_mul_f32 v[38:39], v[38:39], v[82:83] op_sel_hi:[1,0]
	v_pk_mul_f32 v[36:37], v[36:37], v[82:83] op_sel_hi:[1,0]
	global_load_dword v82, v[66:67], off offset:112
	s_waitcnt vmcnt(0)
	v_pk_mul_f32 v[34:35], v[34:35], v[82:83] op_sel_hi:[1,0]
	v_pk_mul_f32 v[32:33], v[32:33], v[82:83] op_sel_hi:[1,0]
	global_load_dword v82, v[66:67], off offset:128
	s_waitcnt vmcnt(0)
	v_pk_mul_f32 v[30:31], v[30:31], v[82:83] op_sel_hi:[1,0]
	v_pk_mul_f32 v[28:29], v[28:29], v[82:83] op_sel_hi:[1,0]
	global_load_dword v82, v[66:67], off offset:144
	s_waitcnt vmcnt(0)
	v_pk_mul_f32 v[26:27], v[26:27], v[82:83] op_sel_hi:[1,0]
	v_pk_mul_f32 v[24:25], v[24:25], v[82:83] op_sel_hi:[1,0]
	global_load_dword v82, v[66:67], off offset:160
	s_waitcnt vmcnt(0)
	v_pk_mul_f32 v[22:23], v[22:23], v[82:83] op_sel_hi:[1,0]
	v_pk_mul_f32 v[20:21], v[20:21], v[82:83] op_sel_hi:[1,0]
	global_load_dword v82, v[66:67], off offset:176
	s_waitcnt vmcnt(0)
	v_pk_mul_f32 v[18:19], v[18:19], v[82:83] op_sel_hi:[1,0]
	v_pk_mul_f32 v[16:17], v[16:17], v[82:83] op_sel_hi:[1,0]
	global_load_dword v82, v[66:67], off offset:192
	s_waitcnt vmcnt(0)
	v_pk_mul_f32 v[14:15], v[14:15], v[82:83] op_sel_hi:[1,0]
	v_pk_mul_f32 v[12:13], v[12:13], v[82:83] op_sel_hi:[1,0]
	global_load_dword v82, v[66:67], off offset:208
	s_waitcnt vmcnt(0)
	v_pk_mul_f32 v[10:11], v[10:11], v[82:83] op_sel_hi:[1,0]
	v_pk_mul_f32 v[8:9], v[8:9], v[82:83] op_sel_hi:[1,0]
	global_load_dword v82, v[66:67], off offset:224
	s_waitcnt vmcnt(0)
	v_pk_mul_f32 v[6:7], v[6:7], v[82:83] op_sel_hi:[1,0]
	global_load_dword v66, v[66:67], off offset:240
	v_pk_mul_f32 v[4:5], v[4:5], v[82:83] op_sel_hi:[1,0]
	s_waitcnt vmcnt(0)
	v_pk_mul_f32 v[2:3], v[2:3], v[66:67] op_sel_hi:[1,0]
	v_pk_mul_f32 v[0:1], v[0:1], v[66:67] op_sel_hi:[1,0]
	s_branch .LBB0_121

.LBB0_364:
	s_lshl_b32 s86, s14, 6
	v_or_b32_e32 v66, s86, v68
	v_ashrrev_i32_e32 v67, 31, v66
	v_mul_lo_u32 v1, s36, v67
	v_mul_lo_u32 v4, s37, v66
	v_mad_u64_u32 v[2:3], s[14:15], s36, v66, 0
	v_add3_u32 v3, v3, v1, v4
	v_lshl_add_u64 v[2:3], v[2:3], 2, s[90:91]
	v_ashrrev_i32_e32 v1, 31, v0
	v_lshl_add_u64 v[0:1], v[0:1], 2, v[2:3]
	s_lshl_b64 s[14:15], s[36:37], 4
	v_lshl_add_u64 v[2:3], v[0:1], 0, s[14:15]
	global_load_dwordx4 v[60:63], v[0:1], off nt
	global_load_dwordx4 v[56:59], v[2:3], off nt
	v_lshl_add_u64 v[0:1], v[2:3], 0, s[14:15]
	v_lshl_add_u64 v[2:3], v[0:1], 0, s[14:15]
	global_load_dwordx4 v[52:55], v[0:1], off nt
	global_load_dwordx4 v[48:51], v[2:3], off nt
	v_lshl_add_u64 v[0:1], v[2:3], 0, s[14:15]
	v_lshl_add_u64 v[2:3], v[0:1], 0, s[14:15]
	global_load_dwordx4 v[44:47], v[0:1], off nt
	global_load_dwordx4 v[40:43], v[2:3], off nt
	v_lshl_add_u64 v[0:1], v[2:3], 0, s[14:15]
	v_lshl_add_u64 v[2:3], v[0:1], 0, s[14:15]
	global_load_dwordx4 v[36:39], v[0:1], off nt
	global_load_dwordx4 v[32:35], v[2:3], off nt
	v_lshl_add_u64 v[0:1], v[2:3], 0, s[14:15]
	global_load_dwordx4 v[28:31], v[0:1], off nt
	v_lshl_add_u64 v[0:1], v[0:1], 0, s[14:15]
	global_load_dwordx4 v[24:27], v[0:1], off nt
	v_lshl_add_u64 v[0:1], v[0:1], 0, s[14:15]
	global_load_dwordx4 v[20:23], v[0:1], off nt
	v_lshl_add_u64 v[0:1], v[0:1], 0, s[14:15]
	global_load_dwordx4 v[16:19], v[0:1], off nt
	v_lshl_add_u64 v[0:1], v[0:1], 0, s[14:15]
	global_load_dwordx4 v[12:15], v[0:1], off nt
	v_lshl_add_u64 v[0:1], v[0:1], 0, s[14:15]
	global_load_dwordx4 v[8:11], v[0:1], off nt
	v_lshl_add_u64 v[0:1], v[0:1], 0, s[14:15]
	global_load_dwordx4 v[4:7], v[0:1], off nt
	v_lshl_add_u64 v[0:1], v[0:1], 0, s[14:15]
	global_load_dwordx4 v[0:3], v[0:1], off nt
	s_cmp_eq_u64 s[30:31], 0
	s_cbranch_scc1 .LBB0_245
	v_lshl_add_u64 v[66:67], v[66:67], 2, s[30:31]
	global_load_dword v82, v[66:67], off
	s_waitcnt vmcnt(0)
	v_pk_mul_f32 v[62:63], v[62:63], v[82:83] op_sel_hi:[1,0]
	v_pk_mul_f32 v[60:61], v[60:61], v[82:83] op_sel_hi:[1,0]
	global_load_dword v82, v[66:67], off offset:16
	s_waitcnt vmcnt(0)
	v_pk_mul_f32 v[58:59], v[58:59], v[82:83] op_sel_hi:[1,0]
	v_pk_mul_f32 v[56:57], v[56:57], v[82:83] op_sel_hi:[1,0]
	global_load_dword v82, v[66:67], off offset:32
	s_waitcnt vmcnt(0)
	v_pk_mul_f32 v[54:55], v[54:55], v[82:83] op_sel_hi:[1,0]
	v_pk_mul_f32 v[52:53], v[52:53], v[82:83] op_sel_hi:[1,0]
	global_load_dword v82, v[66:67], off offset:48
	s_waitcnt vmcnt(0)
	v_pk_mul_f32 v[50:51], v[50:51], v[82:83] op_sel_hi:[1,0]
	v_pk_mul_f32 v[48:49], v[48:49], v[82:83] op_sel_hi:[1,0]
	global_load_dword v82, v[66:67], off offset:64
	s_waitcnt vmcnt(0)
	v_pk_mul_f32 v[46:47], v[46:47], v[82:83] op_sel_hi:[1,0]
	v_pk_mul_f32 v[44:45], v[44:45], v[82:83] op_sel_hi:[1,0]
	global_load_dword v82, v[66:67], off offset:80
	s_waitcnt vmcnt(0)
	v_pk_mul_f32 v[42:43], v[42:43], v[82:83] op_sel_hi:[1,0]
	v_pk_mul_f32 v[40:41], v[40:41], v[82:83] op_sel_hi:[1,0]
	global_load_dword v82, v[66:67], off offset:96
	s_waitcnt vmcnt(0)
	v_pk_mul_f32 v[38:39], v[38:39], v[82:83] op_sel_hi:[1,0]
	v_pk_mul_f32 v[36:37], v[36:37], v[82:83] op_sel_hi:[1,0]
	global_load_dword v82, v[66:67], off offset:112
	s_waitcnt vmcnt(0)
	v_pk_mul_f32 v[34:35], v[34:35], v[82:83] op_sel_hi:[1,0]
	v_pk_mul_f32 v[32:33], v[32:33], v[82:83] op_sel_hi:[1,0]
	global_load_dword v82, v[66:67], off offset:128
	s_waitcnt vmcnt(0)
	v_pk_mul_f32 v[30:31], v[30:31], v[82:83] op_sel_hi:[1,0]
	v_pk_mul_f32 v[28:29], v[28:29], v[82:83] op_sel_hi:[1,0]
	global_load_dword v82, v[66:67], off offset:144
	s_waitcnt vmcnt(0)
	v_pk_mul_f32 v[26:27], v[26:27], v[82:83] op_sel_hi:[1,0]
	v_pk_mul_f32 v[24:25], v[24:25], v[82:83] op_sel_hi:[1,0]
	global_load_dword v82, v[66:67], off offset:160
	s_waitcnt vmcnt(0)
	v_pk_mul_f32 v[22:23], v[22:23], v[82:83] op_sel_hi:[1,0]
	v_pk_mul_f32 v[20:21], v[20:21], v[82:83] op_sel_hi:[1,0]
	global_load_dword v82, v[66:67], off offset:176
	s_waitcnt vmcnt(0)
	v_pk_mul_f32 v[18:19], v[18:19], v[82:83] op_sel_hi:[1,0]
	v_pk_mul_f32 v[16:17], v[16:17], v[82:83] op_sel_hi:[1,0]
	global_load_dword v82, v[66:67], off offset:192
	s_waitcnt vmcnt(0)
	v_pk_mul_f32 v[14:15], v[14:15], v[82:83] op_sel_hi:[1,0]
	v_pk_mul_f32 v[12:13], v[12:13], v[82:83] op_sel_hi:[1,0]
	global_load_dword v82, v[66:67], off offset:208
	s_waitcnt vmcnt(0)
	v_pk_mul_f32 v[10:11], v[10:11], v[82:83] op_sel_hi:[1,0]
	v_pk_mul_f32 v[8:9], v[8:9], v[82:83] op_sel_hi:[1,0]
	global_load_dword v82, v[66:67], off offset:224
	s_waitcnt vmcnt(0)
	v_pk_mul_f32 v[6:7], v[6:7], v[82:83] op_sel_hi:[1,0]
	global_load_dword v66, v[66:67], off offset:240
	v_pk_mul_f32 v[4:5], v[4:5], v[82:83] op_sel_hi:[1,0]
	s_waitcnt vmcnt(0)
	v_pk_mul_f32 v[2:3], v[2:3], v[66:67] op_sel_hi:[1,0]
	v_pk_mul_f32 v[0:1], v[0:1], v[66:67] op_sel_hi:[1,0]
	s_branch .LBB0_245

.LBB0_1238:
	s_lshl_b32 s36, s16, 6
	v_or_b32_e32 v66, s36, v68
	v_ashrrev_i32_e32 v67, 31, v66
	v_mul_lo_u32 v1, s96, v67
	v_mul_lo_u32 v4, s97, v66
	v_mad_u64_u32 v[2:3], s[10:11], s96, v66, 0
	v_add3_u32 v3, v3, v1, v4
	v_lshl_add_u64 v[2:3], v[2:3], 2, s[80:81]
	v_ashrrev_i32_e32 v1, 31, v0
	v_lshl_add_u64 v[0:1], v[0:1], 2, v[2:3]
	s_lshl_b64 s[10:11], s[96:97], 4
	v_lshl_add_u64 v[2:3], v[0:1], 0, s[10:11]
	global_load_dwordx4 v[60:63], v[0:1], off nt
	global_load_dwordx4 v[56:59], v[2:3], off nt
	v_lshl_add_u64 v[0:1], v[2:3], 0, s[10:11]
	v_lshl_add_u64 v[2:3], v[0:1], 0, s[10:11]
	global_load_dwordx4 v[52:55], v[0:1], off nt
	global_load_dwordx4 v[48:51], v[2:3], off nt
	v_lshl_add_u64 v[0:1], v[2:3], 0, s[10:11]
	v_lshl_add_u64 v[2:3], v[0:1], 0, s[10:11]
	global_load_dwordx4 v[44:47], v[0:1], off nt
	global_load_dwordx4 v[40:43], v[2:3], off nt
	v_lshl_add_u64 v[0:1], v[2:3], 0, s[10:11]
	v_lshl_add_u64 v[2:3], v[0:1], 0, s[10:11]
	global_load_dwordx4 v[36:39], v[0:1], off nt
	global_load_dwordx4 v[32:35], v[2:3], off nt
	v_lshl_add_u64 v[0:1], v[2:3], 0, s[10:11]
	global_load_dwordx4 v[28:31], v[0:1], off nt
	v_lshl_add_u64 v[0:1], v[0:1], 0, s[10:11]
	global_load_dwordx4 v[24:27], v[0:1], off nt
	v_lshl_add_u64 v[0:1], v[0:1], 0, s[10:11]
	global_load_dwordx4 v[20:23], v[0:1], off nt
	v_lshl_add_u64 v[0:1], v[0:1], 0, s[10:11]
	global_load_dwordx4 v[16:19], v[0:1], off nt
	v_lshl_add_u64 v[0:1], v[0:1], 0, s[10:11]
	global_load_dwordx4 v[12:15], v[0:1], off nt
	v_lshl_add_u64 v[0:1], v[0:1], 0, s[10:11]
	global_load_dwordx4 v[8:11], v[0:1], off nt
	v_lshl_add_u64 v[0:1], v[0:1], 0, s[10:11]
	global_load_dwordx4 v[4:7], v[0:1], off nt
	v_lshl_add_u64 v[0:1], v[0:1], 0, s[10:11]
	global_load_dwordx4 v[0:3], v[0:1], off nt
	s_cmp_eq_u64 s[42:43], 0
	s_cbranch_scc1 .LBB0_1125
	v_lshl_add_u64 v[66:67], v[66:67], 2, s[42:43]
	global_load_dword v82, v[66:67], off
	s_waitcnt vmcnt(0)
	v_pk_mul_f32 v[62:63], v[62:63], v[82:83] op_sel_hi:[1,0]
	v_pk_mul_f32 v[60:61], v[60:61], v[82:83] op_sel_hi:[1,0]
	global_load_dword v82, v[66:67], off offset:16
	s_waitcnt vmcnt(0)
	v_pk_mul_f32 v[58:59], v[58:59], v[82:83] op_sel_hi:[1,0]
	v_pk_mul_f32 v[56:57], v[56:57], v[82:83] op_sel_hi:[1,0]
	global_load_dword v82, v[66:67], off offset:32
	s_waitcnt vmcnt(0)
	v_pk_mul_f32 v[54:55], v[54:55], v[82:83] op_sel_hi:[1,0]
	v_pk_mul_f32 v[52:53], v[52:53], v[82:83] op_sel_hi:[1,0]
	global_load_dword v82, v[66:67], off offset:48
	s_waitcnt vmcnt(0)
	v_pk_mul_f32 v[50:51], v[50:51], v[82:83] op_sel_hi:[1,0]
	v_pk_mul_f32 v[48:49], v[48:49], v[82:83] op_sel_hi:[1,0]
	global_load_dword v82, v[66:67], off offset:64
	s_waitcnt vmcnt(0)
	v_pk_mul_f32 v[46:47], v[46:47], v[82:83] op_sel_hi:[1,0]
	v_pk_mul_f32 v[44:45], v[44:45], v[82:83] op_sel_hi:[1,0]
	global_load_dword v82, v[66:67], off offset:80
	s_waitcnt vmcnt(0)
	v_pk_mul_f32 v[42:43], v[42:43], v[82:83] op_sel_hi:[1,0]
	v_pk_mul_f32 v[40:41], v[40:41], v[82:83] op_sel_hi:[1,0]
	global_load_dword v82, v[66:67], off offset:96
	s_waitcnt vmcnt(0)
	v_pk_mul_f32 v[38:39], v[38:39], v[82:83] op_sel_hi:[1,0]
	v_pk_mul_f32 v[36:37], v[36:37], v[82:83] op_sel_hi:[1,0]
	global_load_dword v82, v[66:67], off offset:112
	s_waitcnt vmcnt(0)
	v_pk_mul_f32 v[34:35], v[34:35], v[82:83] op_sel_hi:[1,0]
	v_pk_mul_f32 v[32:33], v[32:33], v[82:83] op_sel_hi:[1,0]
	global_load_dword v82, v[66:67], off offset:128
	s_waitcnt vmcnt(0)
	v_pk_mul_f32 v[30:31], v[30:31], v[82:83] op_sel_hi:[1,0]
	v_pk_mul_f32 v[28:29], v[28:29], v[82:83] op_sel_hi:[1,0]
	global_load_dword v82, v[66:67], off offset:144
	s_waitcnt vmcnt(0)
	v_pk_mul_f32 v[26:27], v[26:27], v[82:83] op_sel_hi:[1,0]
	v_pk_mul_f32 v[24:25], v[24:25], v[82:83] op_sel_hi:[1,0]
	global_load_dword v82, v[66:67], off offset:160
	s_waitcnt vmcnt(0)
	v_pk_mul_f32 v[22:23], v[22:23], v[82:83] op_sel_hi:[1,0]
	v_pk_mul_f32 v[20:21], v[20:21], v[82:83] op_sel_hi:[1,0]
	global_load_dword v82, v[66:67], off offset:176
	s_waitcnt vmcnt(0)
	v_pk_mul_f32 v[18:19], v[18:19], v[82:83] op_sel_hi:[1,0]
	v_pk_mul_f32 v[16:17], v[16:17], v[82:83] op_sel_hi:[1,0]
	global_load_dword v82, v[66:67], off offset:192
	s_waitcnt vmcnt(0)
	v_pk_mul_f32 v[14:15], v[14:15], v[82:83] op_sel_hi:[1,0]
	v_pk_mul_f32 v[12:13], v[12:13], v[82:83] op_sel_hi:[1,0]
	global_load_dword v82, v[66:67], off offset:208
	s_waitcnt vmcnt(0)
	v_pk_mul_f32 v[10:11], v[10:11], v[82:83] op_sel_hi:[1,0]
	v_pk_mul_f32 v[8:9], v[8:9], v[82:83] op_sel_hi:[1,0]
	global_load_dword v82, v[66:67], off offset:224
	s_waitcnt vmcnt(0)
	v_pk_mul_f32 v[6:7], v[6:7], v[82:83] op_sel_hi:[1,0]
	global_load_dword v66, v[66:67], off offset:240
	v_pk_mul_f32 v[4:5], v[4:5], v[82:83] op_sel_hi:[1,0]
	s_waitcnt vmcnt(0)
	v_pk_mul_f32 v[2:3], v[2:3], v[66:67] op_sel_hi:[1,0]
	v_pk_mul_f32 v[0:1], v[0:1], v[66:67] op_sel_hi:[1,0]
	s_branch .LBB0_1125

.LBB0_1544:
	s_lshl_b32 s96, s16, 6
	v_or_b32_e32 v66, s96, v68
	v_ashrrev_i32_e32 v67, 31, v66
	v_mul_lo_u32 v1, s94, v67
	v_mul_lo_u32 v4, s95, v66
	v_mad_u64_u32 v[2:3], s[4:5], s94, v66, 0
	v_add3_u32 v3, v3, v1, v4
	v_lshl_add_u64 v[2:3], v[2:3], 2, s[10:11]
	v_ashrrev_i32_e32 v1, 31, v0
	v_lshl_add_u64 v[0:1], v[0:1], 2, v[2:3]
	s_lshl_b64 s[4:5], s[94:95], 4
	v_lshl_add_u64 v[2:3], v[0:1], 0, s[4:5]
	global_load_dwordx4 v[60:63], v[0:1], off nt
	global_load_dwordx4 v[56:59], v[2:3], off nt
	v_lshl_add_u64 v[0:1], v[2:3], 0, s[4:5]
	v_lshl_add_u64 v[2:3], v[0:1], 0, s[4:5]
	global_load_dwordx4 v[52:55], v[0:1], off nt
	global_load_dwordx4 v[48:51], v[2:3], off nt
	v_lshl_add_u64 v[0:1], v[2:3], 0, s[4:5]
	v_lshl_add_u64 v[2:3], v[0:1], 0, s[4:5]
	global_load_dwordx4 v[44:47], v[0:1], off nt
	global_load_dwordx4 v[40:43], v[2:3], off nt
	v_lshl_add_u64 v[0:1], v[2:3], 0, s[4:5]
	v_lshl_add_u64 v[2:3], v[0:1], 0, s[4:5]
	global_load_dwordx4 v[36:39], v[0:1], off nt
	global_load_dwordx4 v[32:35], v[2:3], off nt
	v_lshl_add_u64 v[0:1], v[2:3], 0, s[4:5]
	global_load_dwordx4 v[28:31], v[0:1], off nt
	v_lshl_add_u64 v[0:1], v[0:1], 0, s[4:5]
	global_load_dwordx4 v[24:27], v[0:1], off nt
	v_lshl_add_u64 v[0:1], v[0:1], 0, s[4:5]
	global_load_dwordx4 v[20:23], v[0:1], off nt
	v_lshl_add_u64 v[0:1], v[0:1], 0, s[4:5]
	global_load_dwordx4 v[16:19], v[0:1], off nt
	v_lshl_add_u64 v[0:1], v[0:1], 0, s[4:5]
	global_load_dwordx4 v[12:15], v[0:1], off nt
	v_lshl_add_u64 v[0:1], v[0:1], 0, s[4:5]
	global_load_dwordx4 v[8:11], v[0:1], off nt
	v_lshl_add_u64 v[0:1], v[0:1], 0, s[4:5]
	global_load_dwordx4 v[4:7], v[0:1], off nt
	v_lshl_add_u64 v[0:1], v[0:1], 0, s[4:5]
	global_load_dwordx4 v[0:3], v[0:1], off nt
	s_cmp_eq_u64 s[42:43], 0
	s_cbranch_scc1 .LBB0_1431
	v_lshl_add_u64 v[66:67], v[66:67], 2, s[42:43]
	global_load_dword v82, v[66:67], off
	s_waitcnt vmcnt(0)
	v_pk_mul_f32 v[62:63], v[62:63], v[82:83] op_sel_hi:[1,0]
	v_pk_mul_f32 v[60:61], v[60:61], v[82:83] op_sel_hi:[1,0]
	global_load_dword v82, v[66:67], off offset:16
	s_waitcnt vmcnt(0)
	v_pk_mul_f32 v[58:59], v[58:59], v[82:83] op_sel_hi:[1,0]
	v_pk_mul_f32 v[56:57], v[56:57], v[82:83] op_sel_hi:[1,0]
	global_load_dword v82, v[66:67], off offset:32
	s_waitcnt vmcnt(0)
	v_pk_mul_f32 v[54:55], v[54:55], v[82:83] op_sel_hi:[1,0]
	v_pk_mul_f32 v[52:53], v[52:53], v[82:83] op_sel_hi:[1,0]
	global_load_dword v82, v[66:67], off offset:48
	s_waitcnt vmcnt(0)
	v_pk_mul_f32 v[50:51], v[50:51], v[82:83] op_sel_hi:[1,0]
	v_pk_mul_f32 v[48:49], v[48:49], v[82:83] op_sel_hi:[1,0]
	global_load_dword v82, v[66:67], off offset:64
	s_waitcnt vmcnt(0)
	v_pk_mul_f32 v[46:47], v[46:47], v[82:83] op_sel_hi:[1,0]
	v_pk_mul_f32 v[44:45], v[44:45], v[82:83] op_sel_hi:[1,0]
	global_load_dword v82, v[66:67], off offset:80
	s_waitcnt vmcnt(0)
	v_pk_mul_f32 v[42:43], v[42:43], v[82:83] op_sel_hi:[1,0]
	v_pk_mul_f32 v[40:41], v[40:41], v[82:83] op_sel_hi:[1,0]
	global_load_dword v82, v[66:67], off offset:96
	s_waitcnt vmcnt(0)
	v_pk_mul_f32 v[38:39], v[38:39], v[82:83] op_sel_hi:[1,0]
	v_pk_mul_f32 v[36:37], v[36:37], v[82:83] op_sel_hi:[1,0]
	global_load_dword v82, v[66:67], off offset:112
	s_waitcnt vmcnt(0)
	v_pk_mul_f32 v[34:35], v[34:35], v[82:83] op_sel_hi:[1,0]
	v_pk_mul_f32 v[32:33], v[32:33], v[82:83] op_sel_hi:[1,0]
	global_load_dword v82, v[66:67], off offset:128
	s_waitcnt vmcnt(0)
	v_pk_mul_f32 v[30:31], v[30:31], v[82:83] op_sel_hi:[1,0]
	v_pk_mul_f32 v[28:29], v[28:29], v[82:83] op_sel_hi:[1,0]
	global_load_dword v82, v[66:67], off offset:144
	s_waitcnt vmcnt(0)
	v_pk_mul_f32 v[26:27], v[26:27], v[82:83] op_sel_hi:[1,0]
	v_pk_mul_f32 v[24:25], v[24:25], v[82:83] op_sel_hi:[1,0]
	global_load_dword v82, v[66:67], off offset:160
	s_waitcnt vmcnt(0)
	v_pk_mul_f32 v[22:23], v[22:23], v[82:83] op_sel_hi:[1,0]
	v_pk_mul_f32 v[20:21], v[20:21], v[82:83] op_sel_hi:[1,0]
	global_load_dword v82, v[66:67], off offset:176
	s_waitcnt vmcnt(0)
	v_pk_mul_f32 v[18:19], v[18:19], v[82:83] op_sel_hi:[1,0]
	v_pk_mul_f32 v[16:17], v[16:17], v[82:83] op_sel_hi:[1,0]
	global_load_dword v82, v[66:67], off offset:192
	s_waitcnt vmcnt(0)
	v_pk_mul_f32 v[14:15], v[14:15], v[82:83] op_sel_hi:[1,0]
	v_pk_mul_f32 v[12:13], v[12:13], v[82:83] op_sel_hi:[1,0]
	global_load_dword v82, v[66:67], off offset:208
	s_waitcnt vmcnt(0)
	v_pk_mul_f32 v[10:11], v[10:11], v[82:83] op_sel_hi:[1,0]
	v_pk_mul_f32 v[8:9], v[8:9], v[82:83] op_sel_hi:[1,0]
	global_load_dword v82, v[66:67], off offset:224
	s_waitcnt vmcnt(0)
	v_pk_mul_f32 v[6:7], v[6:7], v[82:83] op_sel_hi:[1,0]
	global_load_dword v66, v[66:67], off offset:240
	v_pk_mul_f32 v[4:5], v[4:5], v[82:83] op_sel_hi:[1,0]
	s_waitcnt vmcnt(0)
	v_pk_mul_f32 v[2:3], v[2:3], v[66:67] op_sel_hi:[1,0]
	v_pk_mul_f32 v[0:1], v[0:1], v[66:67] op_sel_hi:[1,0]
	s_branch .LBB0_1431
